# lr_task tail: the four consecutive row sums fetched with one 16-byte load (were four dependent load/wait/store rounds)
# speedup vs baseline: 1.0296x; 1.0012x over previous
.LBB0_361:
	s_and_b64 vcc, exec, s[4:5]
	s_waitcnt lgkmcnt(0)
	s_barrier
	s_cbranch_vccnz .LBB0_356
	v_or_b32_e32 v12, s11, v15
	v_ashrrev_i32_e32 v13, 31, v12
	v_lshl_add_u64 v[22:23], v[12:13], 2, s[90:91]
	global_load_dwordx4 v[200:203], v[22:23], off
	ds_read_b128 v[18:21], v4
	v_lshlrev_b64 v[22:23], 7, v[12:13]
	v_lshl_add_u64 v[22:23], v[10:11], 0, v[22:23]
	s_waitcnt lgkmcnt(0)
	v_add_f32_e32 v0, v0, v18
	v_add_f32_e32 v13, v1, v19
	v_add_f32_e32 v2, v2, v20
	s_waitcnt vmcnt(0)
	v_fmamk_f32 v17, v200, 0x3a000000, v16
	v_cmp_gt_f32_e32 vcc, s9, v17
	v_mul_f32_e32 v18, 0x4b800000, v17
	s_nop 0
	v_cndmask_b32_e32 v17, v17, v18, vcc
	v_rsq_f32_e32 v17, v17
	s_nop 0
	v_mul_f32_e32 v18, 0x45800000, v17
	v_cndmask_b32_e32 v17, v17, v18, vcc
	v_mul_f32_e32 v0, v0, v17
	global_store_dword v[22:23], v0, off
	v_or_b32_e32 v0, 1, v12
	v_ashrrev_i32_e32 v1, 31, v0
	v_lshl_add_u64 v[18:19], v[0:1], 2, s[90:91]
	v_lshlrev_b64 v[0:1], 7, v[0:1]
	v_lshl_add_u64 v[0:1], v[10:11], 0, v[0:1]
	v_fmamk_f32 v17, v201, 0x3a000000, v16
	v_cmp_gt_f32_e32 vcc, s9, v17
	v_mul_f32_e32 v18, 0x4b800000, v17
	s_nop 0
	v_cndmask_b32_e32 v17, v17, v18, vcc
	v_rsq_f32_e32 v17, v17
	s_nop 0
	v_mul_f32_e32 v18, 0x45800000, v17
	v_cndmask_b32_e32 v17, v17, v18, vcc
	v_mul_f32_e32 v13, v13, v17
	global_store_dword v[0:1], v13, off
	v_or_b32_e32 v0, 2, v12
	v_ashrrev_i32_e32 v1, 31, v0
	v_lshl_add_u64 v[18:19], v[0:1], 2, s[90:91]
	v_lshlrev_b64 v[0:1], 7, v[0:1]
	v_lshl_add_u64 v[0:1], v[10:11], 0, v[0:1]
	v_fmamk_f32 v13, v202, 0x3a000000, v16
	v_cmp_gt_f32_e32 vcc, s9, v13
	v_mul_f32_e32 v17, 0x4b800000, v13
	s_nop 0
	v_cndmask_b32_e32 v13, v13, v17, vcc
	v_rsq_f32_e32 v13, v13
	s_nop 0
	v_mul_f32_e32 v17, 0x45800000, v13
	v_cndmask_b32_e32 v13, v13, v17, vcc
	v_mul_f32_e32 v2, v2, v13
	global_store_dword v[0:1], v2, off
	v_or_b32_e32 v0, 3, v12
	v_ashrrev_i32_e32 v1, 31, v0
	v_add_f32_e32 v12, v3, v21
	v_lshl_add_u64 v[2:3], v[0:1], 2, s[90:91]
	v_lshlrev_b64 v[0:1], 7, v[0:1]
	v_lshl_add_u64 v[0:1], v[10:11], 0, v[0:1]
	v_fmamk_f32 v2, v203, 0x3a000000, v16
	v_cmp_gt_f32_e32 vcc, s9, v2
	v_mul_f32_e32 v3, 0x4b800000, v2
	s_nop 0
	v_cndmask_b32_e32 v2, v2, v3, vcc
	v_rsq_f32_e32 v2, v2
	s_nop 0
	v_mul_f32_e32 v3, 0x45800000, v2
	v_cndmask_b32_e32 v2, v2, v3, vcc
	v_mul_f32_e32 v2, v12, v2
	global_store_dword v[0:1], v2, off
	s_branch .LBB0_356
